# v32 + nt cache policy on the once-read f32 input rows: phase-1 norm loads and the first FFN-down epilogue's f32 residual-base loads
# speedup vs baseline: 1.0013x; 1.0013x over previous
; #define LAS __attribute__((address_space(3)))
; __device__ __forceinline__ u32x2 f32x4_to_h4(f32x4 v) { return __builtin_bit_cast(u32x2, __builtin_convertvector(v, f16x4)); }
; template <bool COMBINE, bool SRC_F32>
; __device__ __forceinline__ void norm_phase(LAS unsigned char* lds, const void* src_lat, const void* src_ctx, _Float16* xw_ctx, const float* part, int nrows, const float* g, const float* modl, int shift_idx, int scale_idx, bf16* HN, int tid, int lane, int wave) {
;     const int gw = blockIdx.x * 8 + wave, NGW = gridDim.x * 8;
;     LAS _Float16* Gs = (LAS _Float16*)lds;
;     LAS _Float16* Ss = Gs + 9 * D;
;     {
;         const f32x4 gg = *(const f32x4*)(g + 4 * tid);
;         f32x4 s1[9], s0[9];
; #pragma unroll
;         for (int r = 0; r < 9; ++r) { s1[r] = *(const f32x4*)(modl + (size_t)r * DMODW + scale_idx * D + 4 * tid); s0[r] = *(const f32x4*)(modl + (size_t)r * DMODW + shift_idx * D + 4 * tid); }
; #pragma unroll
;         for (int r = 0; r < 9; ++r) { *(LAS u32x2*)(Gs + r * D + 4 * tid) = f32x4_to_h4(gg * (1.0f + s1[r])); *(LAS u32x2*)(Ss + r * D + 4 * tid) = f32x4_to_h4(s0[r]); }
.LBB0_146:
	v_readfirstlane_b32 s2, v0
	s_lshr_b32 s2, s2, 6
	s_cmp_lt_i32 s90, 2
	v_writelane_b32 v253, s2, 31
	s_cselect_b64 s[2:3], -1, 0
	s_and_b64 s[4:5], s[2:3], s[6:7]
	s_andn2_b64 vcc, exec, s[4:5]
	v_lshl_add_u32 v228, v0, 3, 0
	s_cbranch_vccnz .LBB0_155
	v_lshlrev_b32_e32 v2, 4, v0
	v_mov_b32_e32 v3, 0
	v_lshl_add_u64 v[76:77], s[88:89], 0, v[2:3]
	v_add_co_u32_e32 v16, vcc, 0x102000, v76
	s_load_dwordx16 s[8:23], s[0:1], 0x0
	s_nop 0
	v_addc_co_u32_e32 v17, vcc, 0, v77, vcc
	v_add_co_u32_e32 v18, vcc, 0x100000, v76
	s_waitcnt lgkmcnt(0)
	global_load_dwordx4 v[4:7], v2, s[20:21]
	v_addc_co_u32_e32 v19, vcc, 0, v77, vcc
	v_add_co_u32_e32 v24, vcc, 0x114000, v76
	global_load_dwordx4 v[8:11], v[16:17], off
	global_load_dwordx4 v[12:15], v[18:19], off
	v_addc_co_u32_e32 v25, vcc, 0, v77, vcc
	v_add_co_u32_e32 v26, vcc, 0x112000, v76
	s_lshl_b32 s4, s86, 3
	s_nop 0
	v_addc_co_u32_e32 v27, vcc, 0, v77, vcc
	v_add_co_u32_e32 v32, vcc, 0x126000, v76
	global_load_dwordx4 v[16:19], v[24:25], off
	global_load_dwordx4 v[20:23], v[26:27], off
	v_addc_co_u32_e32 v33, vcc, 0, v77, vcc
	v_add_co_u32_e32 v34, vcc, 0x124000, v76
	v_readlane_b32 s5, v253, 31
	s_nop 0
	v_addc_co_u32_e32 v35, vcc, 0, v77, vcc
	v_add_co_u32_e32 v40, vcc, 0x138000, v76
	global_load_dwordx4 v[24:27], v[32:33], off
	global_load_dwordx4 v[28:31], v[34:35], off
	v_addc_co_u32_e32 v41, vcc, 0, v77, vcc
	v_add_co_u32_e32 v42, vcc, 0x136000, v76
	s_add_i32 s10, s5, s4
	s_nop 0
	v_addc_co_u32_e32 v43, vcc, 0, v77, vcc
	v_add_co_u32_e32 v48, vcc, 0x14a000, v76
	global_load_dwordx4 v[32:35], v[40:41], off
	global_load_dwordx4 v[36:39], v[42:43], off
	v_addc_co_u32_e32 v49, vcc, 0, v77, vcc
	v_add_co_u32_e32 v50, vcc, 0x148000, v76
	v_add_u32_e32 v2, 0x9000, v228
	s_nop 0
	v_addc_co_u32_e32 v51, vcc, 0, v77, vcc
	v_add_co_u32_e32 v56, vcc, 0x15c000, v76
	global_load_dwordx4 v[40:43], v[48:49], off
	global_load_dwordx4 v[44:47], v[50:51], off
	v_addc_co_u32_e32 v57, vcc, 0, v77, vcc
	v_add_co_u32_e32 v58, vcc, 0x15a000, v76
	s_cmpk_lt_i32 s10, 0x4800
	s_nop 0
	v_addc_co_u32_e32 v59, vcc, 0, v77, vcc
	v_add_co_u32_e32 v64, vcc, 0x16e000, v76
	global_load_dwordx4 v[48:51], v[56:57], off
	global_load_dwordx4 v[52:55], v[58:59], off
	v_addc_co_u32_e32 v65, vcc, 0, v77, vcc
	v_add_co_u32_e32 v66, vcc, 0x16c000, v76
	s_cselect_b64 s[4:5], -1, 0
	s_nop 0
	v_addc_co_u32_e32 v67, vcc, 0, v77, vcc
	global_load_dwordx4 v[56:59], v[64:65], off
	global_load_dwordx4 v[60:63], v[66:67], off
	v_add_co_u32_e32 v64, vcc, 0x180000, v76
	s_cmpk_gt_i32 s10, 0x47ff
	s_nop 0
	v_addc_co_u32_e32 v65, vcc, 0, v77, vcc
	v_add_co_u32_e32 v68, vcc, 0x17e000, v76
	global_load_dwordx4 v[64:67], v[64:65], off
	s_nop 0
	v_addc_co_u32_e32 v69, vcc, 0, v77, vcc
	v_add_co_u32_e32 v72, vcc, 0x192000, v76
	global_load_dwordx4 v[68:71], v[68:69], off
	s_nop 0
	v_addc_co_u32_e32 v73, vcc, 0, v77, vcc
	global_load_dwordx4 v[72:75], v[72:73], off
	v_add_co_u32_e32 v76, vcc, 0x190000, v76
	s_waitcnt vmcnt(16)
	v_pk_add_f32 v[10:11], v[10:11], 1.0 op_sel_hi:[1,0]
	v_addc_co_u32_e32 v77, vcc, 0, v77, vcc
	global_load_dwordx4 v[76:79], v[76:77], off
	v_pk_add_f32 v[8:9], v[8:9], 1.0 op_sel_hi:[1,0]
	v_pk_mul_f32 v[10:11], v[6:7], v[10:11]
	v_pk_mul_f32 v[8:9], v[4:5], v[8:9]
	v_cvt_pk_f16_f32 v11, v10, v11
	v_cvt_pk_f16_f32 v10, v8, v9
	s_waitcnt vmcnt(16)
	v_cvt_pk_f16_f32 v9, v14, v15
	v_cvt_pk_f16_f32 v8, v12, v13
	s_waitcnt vmcnt(15)
	v_pk_add_f32 v[12:13], v[18:19], 1.0 op_sel_hi:[1,0]
	v_pk_add_f32 v[14:15], v[16:17], 1.0 op_sel_hi:[1,0]
	v_pk_mul_f32 v[12:13], v[6:7], v[12:13]
	v_pk_mul_f32 v[14:15], v[4:5], v[14:15]
	v_cvt_pk_f16_f32 v13, v12, v13
	v_cvt_pk_f16_f32 v12, v14, v15
	ds_write2st64_b64 v228, v[10:11], v[12:13] offset1:8
	s_waitcnt vmcnt(14)
	v_cvt_pk_f16_f32 v11, v22, v23
	v_cvt_pk_f16_f32 v10, v20, v21
	s_waitcnt vmcnt(13)
	v_pk_add_f32 v[12:13], v[26:27], 1.0 op_sel_hi:[1,0]
	v_pk_add_f32 v[14:15], v[24:25], 1.0 op_sel_hi:[1,0]
	v_pk_mul_f32 v[12:13], v[6:7], v[12:13]
	v_pk_mul_f32 v[14:15], v[4:5], v[14:15]
	v_cvt_pk_f16_f32 v13, v12, v13
	v_cvt_pk_f16_f32 v12, v14, v15
	s_waitcnt vmcnt(12)
	v_cvt_pk_f16_f32 v15, v30, v31
	v_cvt_pk_f16_f32 v14, v28, v29
	ds_write2st64_b64 v228, v[10:11], v[14:15] offset0:80 offset1:88
	v_mov_b32_e32 v30, v3
	s_waitcnt vmcnt(11)
; #define LAS __attribute__((address_space(3)))
; __device__ __forceinline__ u32x2 f32x4_to_h4(f32x4 v) { return __builtin_bit_cast(u32x2, __builtin_convertvector(v, f16x4)); }
; template <bool COMBINE, bool SRC_F32>
; __device__ __forceinline__ void norm_phase(LAS unsigned char* lds, const void* src_lat, const void* src_ctx, _Float16* xw_ctx, const float* part, int nrows, const float* g, const float* modl, int shift_idx, int scale_idx, bf16* HN, int tid, int lane, int wave) {
;     ...
;         for (int r = 0; r < 9; ++r) { *(LAS u32x2*)(Gs + r * D + 4 * tid) = f32x4_to_h4(gg * (1.0f + s1[r])); *(LAS u32x2*)(Ss + r * D + 4 * tid) = f32x4_to_h4(s0[r]); }
;     }
;     f32x4 v[8], nv[8];
;     ...
;     if (gw < nrows) NORM_LOAD(v, gw);
	v_pk_add_f32 v[10:11], v[34:35], 1.0 op_sel_hi:[1,0]
	v_pk_add_f32 v[14:15], v[32:33], 1.0 op_sel_hi:[1,0]
	v_pk_mul_f32 v[10:11], v[6:7], v[10:11]
	v_pk_mul_f32 v[14:15], v[4:5], v[14:15]
	v_cvt_pk_f16_f32 v11, v10, v11
	v_cvt_pk_f16_f32 v10, v14, v15
	ds_write2st64_b64 v228, v[12:13], v[10:11] offset0:16 offset1:24
	s_waitcnt vmcnt(10)
	v_cvt_pk_f16_f32 v11, v38, v39
	v_cvt_pk_f16_f32 v10, v36, v37
	v_mov_b32_e32 v31, v3
	s_waitcnt vmcnt(9)
	v_pk_add_f32 v[12:13], v[42:43], 1.0 op_sel_hi:[1,0]
	v_pk_add_f32 v[14:15], v[40:41], 1.0 op_sel_hi:[1,0]
	v_pk_mul_f32 v[12:13], v[6:7], v[12:13]
	v_pk_mul_f32 v[14:15], v[4:5], v[14:15]
	v_cvt_pk_f16_f32 v13, v12, v13
	v_cvt_pk_f16_f32 v12, v14, v15
	s_waitcnt vmcnt(8)
	v_cvt_pk_f16_f32 v15, v46, v47
	v_cvt_pk_f16_f32 v14, v44, v45
	ds_write2st64_b64 v228, v[10:11], v[14:15] offset0:96 offset1:104
	v_mov_b32_e32 v42, v3
	s_waitcnt vmcnt(7)
	v_pk_add_f32 v[10:11], v[50:51], 1.0 op_sel_hi:[1,0]
	v_pk_add_f32 v[14:15], v[48:49], 1.0 op_sel_hi:[1,0]
	v_pk_mul_f32 v[10:11], v[6:7], v[10:11]
	v_pk_mul_f32 v[14:15], v[4:5], v[14:15]
	v_cvt_pk_f16_f32 v11, v10, v11
	v_cvt_pk_f16_f32 v10, v14, v15
	ds_write2st64_b64 v228, v[12:13], v[10:11] offset0:32 offset1:40
	s_waitcnt vmcnt(6)
	v_cvt_pk_f16_f32 v11, v54, v55
	s_waitcnt vmcnt(5)
	v_pk_add_f32 v[12:13], v[58:59], 1.0 op_sel_hi:[1,0]
	v_pk_add_f32 v[14:15], v[56:57], 1.0 op_sel_hi:[1,0]
	v_pk_mul_f32 v[12:13], v[6:7], v[12:13]
	v_pk_mul_f32 v[14:15], v[4:5], v[14:15]
	v_cvt_pk_f16_f32 v10, v52, v53
	v_cvt_pk_f16_f32 v13, v12, v13
	v_cvt_pk_f16_f32 v12, v14, v15
	s_waitcnt vmcnt(4)
	v_cvt_pk_f16_f32 v15, v62, v63
	v_cvt_pk_f16_f32 v14, v60, v61
	ds_write2st64_b64 v228, v[10:11], v[14:15] offset0:112 offset1:120
	s_waitcnt vmcnt(3)
	v_pk_add_f32 v[10:11], v[66:67], 1.0 op_sel_hi:[1,0]
	v_pk_add_f32 v[14:15], v[64:65], 1.0 op_sel_hi:[1,0]
	v_pk_mul_f32 v[10:11], v[6:7], v[10:11]
	v_pk_mul_f32 v[14:15], v[4:5], v[14:15]
	v_cvt_pk_f16_f32 v11, v10, v11
	v_cvt_pk_f16_f32 v10, v14, v15
	ds_write2st64_b64 v228, v[12:13], v[10:11] offset0:48 offset1:56
	s_waitcnt vmcnt(1)
	v_pk_add_f32 v[12:13], v[74:75], 1.0 op_sel_hi:[1,0]
	v_pk_add_f32 v[14:15], v[72:73], 1.0 op_sel_hi:[1,0]
	v_pk_mul_f32 v[6:7], v[6:7], v[12:13]
	v_pk_mul_f32 v[4:5], v[4:5], v[14:15]
	v_cvt_pk_f16_f32 v11, v70, v71
	v_cvt_pk_f16_f32 v10, v68, v69
	v_cvt_pk_f16_f32 v7, v6, v7
	v_cvt_pk_f16_f32 v6, v4, v5
	s_waitcnt vmcnt(0)
	v_cvt_pk_f16_f32 v5, v78, v79
	v_cvt_pk_f16_f32 v4, v76, v77
	ds_write2st64_b64 v228, v[6:7], v[8:9] offset0:64 offset1:72
	ds_write2st64_b64 v2, v[10:11], v[4:5] offset0:56 offset1:64
	v_mov_b32_e32 v2, v3
	v_mov_b32_e32 v4, v3
	v_mov_b32_e32 v5, v3
	v_mov_b32_e32 v62, v3
	v_mov_b32_e32 v63, v3
	v_mov_b32_e32 v64, v3
	v_mov_b32_e32 v65, v3
	v_mov_b32_e32 v58, v3
	v_mov_b32_e32 v59, v3
	v_mov_b32_e32 v60, v3
	v_mov_b32_e32 v61, v3
	v_mov_b32_e32 v54, v3
	v_mov_b32_e32 v55, v3
	v_mov_b32_e32 v56, v3
	v_mov_b32_e32 v57, v3
	v_mov_b32_e32 v43, v3
	v_mov_b32_e32 v44, v3
	v_mov_b32_e32 v45, v3
	v_mov_b32_e32 v32, v3
	v_mov_b32_e32 v33, v3
	v_mov_b32_e32 v14, v3
	v_mov_b32_e32 v15, v3
	v_mov_b32_e32 v16, v3
	v_mov_b32_e32 v17, v3
	v_mov_b32_e32 v6, v3
	v_mov_b32_e32 v7, v3
	v_mov_b32_e32 v8, v3
	v_mov_b32_e32 v9, v3
	s_cbranch_scc1 .LBB0_149
	s_load_dwordx16 s[12:27], s[0:1], 0x0
	s_ashr_i32 s6, s10, 31
	s_add_i32 s8, s10, 0xffffc000
	s_cmpk_lt_i32 s10, 0x4000
	s_cselect_b32 s7, s6, 0
	s_cselect_b32 s6, s10, s8
	s_waitcnt lgkmcnt(0)
	s_cselect_b32 s9, s13, s17
	s_cselect_b32 s11, s12, s16
	s_lshl_b64 s[6:7], s[6:7], 13
	s_add_u32 s6, s11, s6
	s_addc_u32 s7, s9, s7
	v_lshlrev_b32_e32 v6, 4, v1
	v_mov_b32_e32 v7, 0
	v_lshl_add_u64 v[8:9], s[6:7], 0, v[6:7]
	global_load_dwordx4 v[2:5], v6, s[6:7] nt
	global_load_dwordx4 v[62:65], v6, s[6:7] offset:1024 nt
	global_load_dwordx4 v[58:61], v6, s[6:7] offset:2048 nt
	global_load_dwordx4 v[54:57], v6, s[6:7] offset:3072 nt
	s_movk_i32 s6, 0x1000
	v_add_co_u32_e32 v10, vcc, s6, v8
	s_nop 1
	v_addc_co_u32_e32 v11, vcc, 0, v9, vcc
	global_load_dwordx4 v[42:45], v[10:11], off nt
	global_load_dwordx4 v[30:33], v[10:11], off offset:1024 nt
	global_load_dwordx4 v[14:17], v[10:11], off offset:2048 nt
	global_load_dwordx4 v[6:9], v[10:11], off offset:3072 nt

; __device__ __forceinline__ void lds_barrier() { asm volatile("s_waitcnt lgkmcnt(0)" ::: "memory"); __builtin_amdgcn_s_barrier(); asm volatile("" ::: "memory"); }
; template <bool COMBINE, bool SRC_F32>
; __device__ __forceinline__ void norm_phase(LAS unsigned char* lds, const void* src_lat, const void* src_ctx, _Float16* xw_ctx, const float* part, int nrows, const float* g, const float* modl, int shift_idx, int scale_idx, bf16* HN, int tid, int lane, int wave) {
;     ...
;     if (gw < nrows) NORM_LOAD(v, gw);
;     lds_barrier();
;     for (int row = gw; row < nrows; row += NGW) {
;         if (row + NGW < nrows) NORM_LOAD(nv, row + NGW);
.LBB0_152:
	s_add_i32 s11, s10, s4
	s_cmpk_gt_i32 s11, 0x47ff
	s_cselect_b64 s[12:13], -1, 0
	s_and_b64 vcc, exec, s[12:13]
	s_cbranch_vccnz .LBB0_151
	s_load_dwordx16 s[16:31], s[0:1], 0x0
	s_ashr_i32 s6, s11, 31
	s_add_i32 s14, s11, 0xffffc000
	s_cmpk_lt_i32 s11, 0x4000
	s_cselect_b32 s7, s6, 0
	s_cselect_b32 s6, s11, s14
	s_waitcnt lgkmcnt(0)
	s_cselect_b32 s15, s17, s21
	s_cselect_b32 s16, s16, s20
	s_lshl_b64 s[6:7], s[6:7], 13
	s_add_u32 s6, s16, s6
	s_addc_u32 s7, s15, s7
	global_load_dwordx4 v[10:13], v70, s[6:7] nt
	global_load_dwordx4 v[18:21], v70, s[6:7] offset:1024 nt
	global_load_dwordx4 v[22:25], v70, s[6:7] offset:2048 nt
	global_load_dwordx4 v[26:29], v70, s[6:7] offset:3072 nt
	global_load_dwordx4 v[34:37], v71, s[6:7] nt
	global_load_dwordx4 v[38:41], v72, s[6:7] nt
	global_load_dwordx4 v[46:49], v73, s[6:7] nt
	global_load_dwordx4 v[50:53], v74, s[6:7] nt
	s_branch .LBB0_151

; #define GAS __attribute__((address_space(1)))
;     __device__ __forceinline__ void operator()(const f32x4 (&acc)[2][2][4][2], const pg8::Unit& u, int wr, int wc, int fr, int fq) const {
;         const float coef = __builtin_bit_cast(float, __builtin_amdgcn_readfirstlane(__builtin_bit_cast(int, this->coef)));
;         GAS float* const part = (GAS float*)(((unsigned long long)(unsigned)__builtin_amdgcn_readfirstlane((int)((unsigned long long)this->part >> 32)) << 32) | (unsigned)__builtin_amdgcn_readfirstlane((int)(unsigned long long)this->part));
;         const int row0 = u.pm * 256 + wr * 64 + fr, col0 = u.pn * 256 + wc * 32 + 8 * fq;
;         const int r = u.pm < 64 ? (u.pm >> 3) : 8;
;         const float* gv = gate + (size_t)r * DMODW + col0;
;         f32x4 gvv[2][2];
; #pragma unroll
;         for (int bj = 0; bj < 2; ++bj)
; #pragma unroll
;             for (int n = 0; n < 2; ++n) gvv[bj][n] = *(const f32x4*)(gv + bj * 128 + 4 * n) * coef;
;     ...
;         } else {
; #pragma unroll
;             for (int ai = 0; ai < 2; ++ai)
; #pragma unroll
;                 for (int mh = 0; mh < 2; ++mh) {
;                     f32x4 b[2][2][2];
; #pragma unroll
;                     for (int mm = 0; mm < 2; ++mm)
; #pragma unroll
;                         for (int bj = 0; bj < 2; ++bj) { const size_t ro = (size_t)(ai * 128 + (2 * mh + mm) * 16) * D + bj * 128;
;                             b[mm][bj][0] = *(const f32x4*)((const float*)bsel + eo + ro); b[mm][bj][1] = *(const f32x4*)((const float*)bsel + eo + ro + 4); }
; #pragma unroll
;                     for (int mm = 0; mm < 2; ++mm)
; #pragma unroll
;                         for (int bj = 0; bj < 2; ++bj) { const size_t ro = (size_t)(ai * 128 + (2 * mh + mm) * 16) * D + bj * 128;
;                             const f32x4 v0 = b[mm][bj][0] + gvv[bj][0] * acc[ai][bj][2 * mh + mm][0], v1 = b[mm][bj][1] + gvv[bj][1] * acc[ai][bj][2 * mh + mm][1];
;                             if constexpr (OUT_F32) { *(f32x4*)((float*)out + oo + ro) = v0; *(f32x4*)((float*)out + oo + ro + 4) = v1; }
;                             else { const u32x2 h0 = f32x4_to_h4(v0), h1 = f32x4_to_h4(v1); *(u32x4*)((_Float16*)out + oo + ro) = (u32x4){h0.x, h0.y, h1.x, h1.y}; } }
;                     asm volatile("" ::: "memory");
;                 }
.LBB0_398:
	s_lshl_b64 s[18:19], s[18:19], 2
	v_lshl_or_b32 v20, s45, 8, v189
	s_add_u32 s18, s30, s18
	s_addc_u32 s19, s31, s19
	v_ashrrev_i32_e32 v21, 31, v20
	v_lshl_add_u64 v[14:15], v[20:21], 2, s[18:19]
	global_load_dwordx4 v[10:13], v[14:15], off offset:16
	global_load_dwordx4 v[2:5], v[14:15], off
	v_lshl_add_u32 v18, s46, 8, v187
	s_mov_b64 s[18:19], -1
	s_cmp_lt_i32 s41, 2
	v_ashrrev_i32_e32 v19, 31, v18
	s_waitcnt vmcnt(0)
	v_pk_mul_f32 v[6:7], v[4:5], s[12:13] op_sel_hi:[1,0]
	v_pk_mul_f32 v[8:9], v[2:3], s[12:13] op_sel_hi:[1,0]
	v_pk_mul_f32 v[2:3], v[12:13], s[12:13] op_sel_hi:[1,0]
	v_pk_mul_f32 v[4:5], v[10:11], s[12:13] op_sel_hi:[1,0]
	global_load_dwordx4 v[22:25], v[14:15], off offset:528
	global_load_dwordx4 v[10:13], v[14:15], off offset:512
	s_waitcnt vmcnt(0)
	v_pk_mul_f32 v[14:15], v[12:13], s[12:13] op_sel_hi:[1,0]
	v_pk_mul_f32 v[16:17], v[10:11], s[12:13] op_sel_hi:[1,0]
	v_pk_mul_f32 v[10:11], v[24:25], s[12:13] op_sel_hi:[1,0]
	v_pk_mul_f32 v[12:13], v[22:23], s[12:13] op_sel_hi:[1,0]
	s_cbranch_scc0 .LBB0_401
	v_add_u32_e32 v22, 0xffffc000, v18
	v_cndmask_b32_e32 v22, v22, v18, vcc
	v_readlane_b32 s68, v253, 10
	v_ashrrev_i32_e32 v23, 31, v22
	s_and_b64 s[18:19], vcc, exec
	v_readlane_b32 s69, v253, 11
	v_readlane_b32 s72, v253, 14
	v_readlane_b32 s73, v253, 15
	s_cselect_b32 s19, s69, s73
	s_cselect_b32 s18, s68, s72
	v_lshlrev_b64 v[22:23], 13, v[22:23]
	v_lshl_add_u64 v[22:23], s[18:19], 0, v[22:23]
	v_lshl_add_u64 v[24:25], v[20:21], 2, v[22:23]
	global_load_dwordx4 v[26:29], v[24:25], off offset:16 nt
	global_load_dwordx4 v[30:33], v[24:25], off nt
	global_load_dwordx4 v[178:181], v[24:25], off offset:528 nt
	global_load_dwordx4 v[182:185], v[24:25], off offset:512 nt
	s_mov_b64 s[18:19], 0x20000
	v_add_co_u32_e32 v202, vcc, s39, v24
	v_lshl_add_u64 v[198:199], v[24:25], 0, s[18:19]
	s_nop 0
	v_addc_co_u32_e32 v203, vcc, 0, v25, vcc
	global_load_dwordx4 v[194:197], v[202:203], off nt
	s_nop 0
	global_load_dwordx4 v[198:201], v[198:199], off offset:16 nt
	s_mov_b64 s[18:19], 0x20200
	v_lshl_add_u64 v[206:207], v[24:25], 0, s[18:19]
	global_load_dwordx4 v[202:205], v[202:203], off offset:512 nt
	s_nop 0
	global_load_dwordx4 v[206:209], v[206:207], off offset:16 nt
	v_readlane_b32 s18, v253, 52
	v_lshlrev_b64 v[22:23], 12, v[18:19]
	v_readlane_b32 s19, v253, 53
	s_mov_b32 s4, 0x10000
	v_readlane_b32 s70, v253, 12
	v_lshl_add_u64 v[22:23], s[18:19], 0, v[22:23]
	v_lshl_add_u64 v[22:23], v[20:21], 1, v[22:23]
	s_mov_b64 s[18:19], 0x40000
	v_readlane_b32 s71, v253, 13
	v_readlane_b32 s74, v253, 16
	v_readlane_b32 s75, v253, 17
	v_readlane_b32 s76, v253, 18
	v_readlane_b32 s77, v253, 19
	v_readlane_b32 s78, v253, 20
	v_readlane_b32 s79, v253, 21
	v_readlane_b32 s80, v253, 22
	v_readlane_b32 s81, v253, 23
	v_readlane_b32 s82, v253, 24
	v_readlane_b32 s83, v253, 25
	s_waitcnt vmcnt(7)
	v_pk_fma_f32 v[28:29], v[156:157], v[2:3], v[28:29]
	s_waitcnt vmcnt(6)
	v_pk_fma_f32 v[32:33], v[160:161], v[6:7], v[32:33]
	v_pk_fma_f32 v[30:31], v[158:159], v[8:9], v[30:31]
	v_pk_fma_f32 v[210:211], v[154:155], v[4:5], v[26:27]
	v_cvt_pk_f16_f32 v27, v32, v33
	v_cvt_pk_f16_f32 v26, v30, v31
	v_cvt_pk_f16_f32 v29, v28, v29
	v_cvt_pk_f16_f32 v28, v210, v211
	global_store_dwordx4 v[22:23], v[26:29], off
	s_waitcnt vmcnt(6)
	v_pk_fma_f32 v[30:31], v[140:141], v[10:11], v[180:181]
	v_pk_fma_f32 v[32:33], v[138:139], v[12:13], v[178:179]
	s_waitcnt vmcnt(5)
	v_pk_fma_f32 v[26:27], v[148:149], v[14:15], v[184:185]
	v_pk_fma_f32 v[28:29], v[146:147], v[16:17], v[182:183]
	v_cvt_pk_f16_f32 v27, v26, v27
	v_cvt_pk_f16_f32 v26, v28, v29
	v_cvt_pk_f16_f32 v29, v30, v31
	v_cvt_pk_f16_f32 v28, v32, v33
	global_store_dwordx4 v[22:23], v[26:29], off offset:256
	s_waitcnt vmcnt(4)
	v_pk_fma_f32 v[30:31], v[144:145], v[2:3], v[200:201]
	v_pk_fma_f32 v[32:33], v[142:143], v[4:5], v[198:199]
	v_pk_fma_f32 v[26:27], v[152:153], v[6:7], v[196:197]
	v_pk_fma_f32 v[28:29], v[150:151], v[8:9], v[194:195]
	v_cvt_pk_f16_f32 v27, v26, v27
	v_cvt_pk_f16_f32 v26, v28, v29
	v_cvt_pk_f16_f32 v29, v30, v31
	v_add_co_u32_e32 v30, vcc, s4, v22
	v_cvt_pk_f16_f32 v28, v32, v33
	s_nop 0
	v_addc_co_u32_e32 v31, vcc, 0, v23, vcc
	global_store_dwordx4 v[30:31], v[26:29], off
	s_waitcnt vmcnt(3)
	v_pk_fma_f32 v[32:33], v[124:125], v[10:11], v[208:209]
	v_pk_fma_f32 v[178:179], v[122:123], v[12:13], v[206:207]
	v_pk_fma_f32 v[26:27], v[132:133], v[14:15], v[204:205]
	v_pk_fma_f32 v[28:29], v[130:131], v[16:17], v[202:203]
	v_cvt_pk_f16_f32 v27, v26, v27
	v_cvt_pk_f16_f32 v26, v28, v29
	v_cvt_pk_f16_f32 v29, v32, v33
	v_cvt_pk_f16_f32 v28, v178, v179
	s_mov_b32 s4, 0x40000
	global_store_dwordx4 v[30:31], v[26:29], off offset:256
	v_add_co_u32_e32 v178, vcc, s4, v24
	v_lshl_add_u64 v[30:31], v[24:25], 0, s[18:19]
	s_nop 0
	v_addc_co_u32_e32 v179, vcc, 0, v25, vcc
	global_load_dwordx4 v[26:29], v[178:179], off nt
	s_nop 0
	global_load_dwordx4 v[30:33], v[30:31], off offset:16 nt
	s_mov_b64 s[18:19], 0x40200
	v_lshl_add_u64 v[182:183], v[24:25], 0, s[18:19]
	s_mov_b32 s4, 0x60000
	global_load_dwordx4 v[178:181], v[178:179], off offset:512 nt
	s_nop 0
	global_load_dwordx4 v[182:185], v[182:183], off offset:16 nt
	s_mov_b64 s[18:19], 0x60000
	v_add_co_u32_e32 v202, vcc, s4, v24
	v_lshl_add_u64 v[198:199], v[24:25], 0, s[18:19]
	s_nop 0
	v_addc_co_u32_e32 v203, vcc, 0, v25, vcc
	global_load_dwordx4 v[194:197], v[202:203], off nt
	s_nop 0
	global_load_dwordx4 v[198:201], v[198:199], off offset:16 nt
	s_mov_b64 s[18:19], 0x60200
	v_lshl_add_u64 v[206:207], v[24:25], 0, s[18:19]
	global_load_dwordx4 v[202:205], v[202:203], off offset:512 nt
	s_nop 0
	global_load_dwordx4 v[206:209], v[206:207], off offset:16 nt
	s_mov_b32 s4, 0x30000
	s_mov_b64 s[18:19], 0x100000
	s_waitcnt vmcnt(7)
; __device__ __forceinline__ u32x2 f32x4_to_h4(f32x4 v) { return __builtin_bit_cast(u32x2, __builtin_convertvector(v, f16x4)); }
;     __device__ __forceinline__ void operator()(const f32x4 (&acc)[2][2][4][2], const pg8::Unit& u, int wr, int wc, int fr, int fq) const {
;     ...
;         } else {
; #pragma unroll
;             for (int ai = 0; ai < 2; ++ai)
; #pragma unroll
;                 for (int mh = 0; mh < 2; ++mh) {
;                     f32x4 b[2][2][2];
; #pragma unroll
;                     for (int mm = 0; mm < 2; ++mm)
; #pragma unroll
;                         for (int bj = 0; bj < 2; ++bj) { const size_t ro = (size_t)(ai * 128 + (2 * mh + mm) * 16) * D + bj * 128;
;                             b[mm][bj][0] = *(const f32x4*)((const float*)bsel + eo + ro); b[mm][bj][1] = *(const f32x4*)((const float*)bsel + eo + ro + 4); }
; #pragma unroll
;                     for (int mm = 0; mm < 2; ++mm)
; #pragma unroll
;                         for (int bj = 0; bj < 2; ++bj) { const size_t ro = (size_t)(ai * 128 + (2 * mh + mm) * 16) * D + bj * 128;
;                             const f32x4 v0 = b[mm][bj][0] + gvv[bj][0] * acc[ai][bj][2 * mh + mm][0], v1 = b[mm][bj][1] + gvv[bj][1] * acc[ai][bj][2 * mh + mm][1];
;                             if constexpr (OUT_F32) { *(f32x4*)((float*)out + oo + ro) = v0; *(f32x4*)((float*)out + oo + ro + 4) = v1; }
;                             else { const u32x2 h0 = f32x4_to_h4(v0), h1 = f32x4_to_h4(v1); *(u32x4*)((_Float16*)out + oo + ro) = (u32x4){h0.x, h0.y, h1.x, h1.y}; } }
;                     asm volatile("" ::: "memory");
;                 }
	v_pk_fma_f32 v[28:29], v[136:137], v[6:7], v[28:29]
	s_waitcnt vmcnt(6)
	v_pk_fma_f32 v[30:31], v[126:127], v[4:5], v[30:31]
	v_pk_fma_f32 v[210:211], v[134:135], v[8:9], v[26:27]
	v_pk_fma_f32 v[32:33], v[128:129], v[2:3], v[32:33]
	v_cvt_pk_f16_f32 v27, v28, v29
	v_cvt_pk_f16_f32 v28, v30, v31
	v_add_co_u32_e32 v30, vcc, s39, v22
	v_cvt_pk_f16_f32 v26, v210, v211
	v_cvt_pk_f16_f32 v29, v32, v33
	v_addc_co_u32_e32 v31, vcc, 0, v23, vcc
	global_store_dwordx4 v[30:31], v[26:29], off
	s_waitcnt vmcnt(5)
	v_pk_fma_f32 v[32:33], v[108:109], v[10:11], v[184:185]
	v_pk_fma_f32 v[26:27], v[116:117], v[14:15], v[180:181]
	v_pk_fma_f32 v[28:29], v[114:115], v[16:17], v[178:179]
	v_pk_fma_f32 v[178:179], v[106:107], v[12:13], v[182:183]
	v_cvt_pk_f16_f32 v27, v26, v27
	v_cvt_pk_f16_f32 v26, v28, v29
	v_cvt_pk_f16_f32 v29, v32, v33
	v_cvt_pk_f16_f32 v28, v178, v179
	global_store_dwordx4 v[30:31], v[26:29], off offset:256
	s_waitcnt vmcnt(4)
	v_pk_fma_f32 v[30:31], v[112:113], v[2:3], v[200:201]
	v_pk_fma_f32 v[32:33], v[110:111], v[4:5], v[198:199]
	v_pk_fma_f32 v[26:27], v[120:121], v[6:7], v[196:197]
	v_pk_fma_f32 v[28:29], v[118:119], v[8:9], v[194:195]
	v_cvt_pk_f16_f32 v27, v26, v27
	v_cvt_pk_f16_f32 v26, v28, v29
	v_cvt_pk_f16_f32 v29, v30, v31
	v_add_co_u32_e32 v30, vcc, s4, v22
	v_cvt_pk_f16_f32 v28, v32, v33
	s_nop 0
	v_addc_co_u32_e32 v31, vcc, 0, v23, vcc
	global_store_dwordx4 v[30:31], v[26:29], off
	s_waitcnt vmcnt(3)
	v_pk_fma_f32 v[32:33], v[100:101], v[10:11], v[208:209]
	v_pk_fma_f32 v[178:179], v[98:99], v[12:13], v[206:207]
	v_pk_fma_f32 v[26:27], v[104:105], v[14:15], v[204:205]
	v_pk_fma_f32 v[28:29], v[102:103], v[16:17], v[202:203]
	v_cvt_pk_f16_f32 v27, v26, v27
	v_cvt_pk_f16_f32 v26, v28, v29
	v_cvt_pk_f16_f32 v29, v32, v33
	v_cvt_pk_f16_f32 v28, v178, v179
	s_mov_b32 s4, 0x100000
	global_store_dwordx4 v[30:31], v[26:29], off offset:256
	v_add_co_u32_e32 v178, vcc, s4, v24
	v_lshl_add_u64 v[30:31], v[24:25], 0, s[18:19]
	s_nop 0
	v_addc_co_u32_e32 v179, vcc, 0, v25, vcc
	global_load_dwordx4 v[26:29], v[178:179], off nt
	s_nop 0
	global_load_dwordx4 v[30:33], v[30:31], off offset:16 nt
	s_mov_b64 s[18:19], 0x100200
	v_lshl_add_u64 v[182:183], v[24:25], 0, s[18:19]
	s_mov_b32 s4, 0x120000
	global_load_dwordx4 v[178:181], v[178:179], off offset:512 nt
	s_nop 0
	global_load_dwordx4 v[182:185], v[182:183], off offset:16 nt
	s_mov_b64 s[18:19], 0x120000
	v_add_co_u32_e32 v202, vcc, s4, v24
	v_lshl_add_u64 v[198:199], v[24:25], 0, s[18:19]
	s_nop 0
	v_addc_co_u32_e32 v203, vcc, 0, v25, vcc
	global_load_dwordx4 v[194:197], v[202:203], off nt
	s_nop 0
	global_load_dwordx4 v[198:201], v[198:199], off offset:16 nt
	s_mov_b64 s[18:19], 0x120200
	v_lshl_add_u64 v[206:207], v[24:25], 0, s[18:19]
	global_load_dwordx4 v[202:205], v[202:203], off offset:512 nt
	s_nop 0
	global_load_dwordx4 v[206:209], v[206:207], off offset:16 nt
	s_mov_b32 s4, 0x80000
	s_mov_b64 s[18:19], 0x140000
	s_waitcnt vmcnt(7)
	v_pk_fma_f32 v[28:29], v[96:97], v[6:7], v[28:29]
	s_waitcnt vmcnt(6)
	v_pk_fma_f32 v[30:31], v[90:91], v[4:5], v[30:31]
	v_pk_fma_f32 v[210:211], v[94:95], v[8:9], v[26:27]
	v_pk_fma_f32 v[32:33], v[92:93], v[2:3], v[32:33]
	v_cvt_pk_f16_f32 v27, v28, v29
	v_cvt_pk_f16_f32 v28, v30, v31
	v_add_co_u32_e32 v30, vcc, s4, v22
	v_cvt_pk_f16_f32 v26, v210, v211
	v_cvt_pk_f16_f32 v29, v32, v33
	v_addc_co_u32_e32 v31, vcc, 0, v23, vcc
	global_store_dwordx4 v[30:31], v[26:29], off
	s_waitcnt vmcnt(5)
	v_pk_fma_f32 v[32:33], v[76:77], v[10:11], v[184:185]
	s_mov_b32 s4, 0x90000
	v_pk_fma_f32 v[26:27], v[84:85], v[14:15], v[180:181]
	v_pk_fma_f32 v[28:29], v[82:83], v[16:17], v[178:179]
	v_pk_fma_f32 v[178:179], v[74:75], v[12:13], v[182:183]
	v_cvt_pk_f16_f32 v27, v26, v27
	v_cvt_pk_f16_f32 v26, v28, v29
	v_cvt_pk_f16_f32 v29, v32, v33
	v_cvt_pk_f16_f32 v28, v178, v179
	global_store_dwordx4 v[30:31], v[26:29], off offset:256
	s_waitcnt vmcnt(4)
; __device__ __forceinline__ u32x2 f32x4_to_h4(f32x4 v) { return __builtin_bit_cast(u32x2, __builtin_convertvector(v, f16x4)); }
;     __device__ __forceinline__ void operator()(const f32x4 (&acc)[2][2][4][2], const pg8::Unit& u, int wr, int wc, int fr, int fq) const {
;     ...
;         } else {
; #pragma unroll
;             for (int ai = 0; ai < 2; ++ai)
; #pragma unroll
;                 for (int mh = 0; mh < 2; ++mh) {
;                     f32x4 b[2][2][2];
; #pragma unroll
;                     for (int mm = 0; mm < 2; ++mm)
; #pragma unroll
;                         for (int bj = 0; bj < 2; ++bj) { const size_t ro = (size_t)(ai * 128 + (2 * mh + mm) * 16) * D + bj * 128;
;                             b[mm][bj][0] = *(const f32x4*)((const float*)bsel + eo + ro); b[mm][bj][1] = *(const f32x4*)((const float*)bsel + eo + ro + 4); }
; #pragma unroll
;                     for (int mm = 0; mm < 2; ++mm)
; #pragma unroll
;                         for (int bj = 0; bj < 2; ++bj) { const size_t ro = (size_t)(ai * 128 + (2 * mh + mm) * 16) * D + bj * 128;
;                             const f32x4 v0 = b[mm][bj][0] + gvv[bj][0] * acc[ai][bj][2 * mh + mm][0], v1 = b[mm][bj][1] + gvv[bj][1] * acc[ai][bj][2 * mh + mm][1];
;                             if constexpr (OUT_F32) { *(f32x4*)((float*)out + oo + ro) = v0; *(f32x4*)((float*)out + oo + ro + 4) = v1; }
;                             else { const u32x2 h0 = f32x4_to_h4(v0), h1 = f32x4_to_h4(v1); *(u32x4*)((_Float16*)out + oo + ro) = (u32x4){h0.x, h0.y, h1.x, h1.y}; } }
;                     asm volatile("" ::: "memory");
;                 }
	v_pk_fma_f32 v[30:31], v[80:81], v[2:3], v[200:201]
	v_pk_fma_f32 v[32:33], v[78:79], v[4:5], v[198:199]
	v_pk_fma_f32 v[26:27], v[88:89], v[6:7], v[196:197]
	v_pk_fma_f32 v[28:29], v[86:87], v[8:9], v[194:195]
	v_cvt_pk_f16_f32 v27, v26, v27
	v_cvt_pk_f16_f32 v26, v28, v29
	v_cvt_pk_f16_f32 v29, v30, v31
	v_add_co_u32_e32 v30, vcc, s4, v22
	v_cvt_pk_f16_f32 v28, v32, v33
	s_nop 0
	v_addc_co_u32_e32 v31, vcc, 0, v23, vcc
	global_store_dwordx4 v[30:31], v[26:29], off
	s_waitcnt vmcnt(3)
	v_pk_fma_f32 v[32:33], v[60:61], v[10:11], v[208:209]
	v_pk_fma_f32 v[178:179], v[58:59], v[12:13], v[206:207]
	v_pk_fma_f32 v[26:27], v[68:69], v[14:15], v[204:205]
	v_pk_fma_f32 v[28:29], v[66:67], v[16:17], v[202:203]
	v_cvt_pk_f16_f32 v27, v26, v27
	v_cvt_pk_f16_f32 v26, v28, v29
	v_cvt_pk_f16_f32 v29, v32, v33
	v_cvt_pk_f16_f32 v28, v178, v179
	s_mov_b32 s4, 0x140000
	global_store_dwordx4 v[30:31], v[26:29], off offset:256
	v_add_co_u32_e32 v178, vcc, s4, v24
	v_lshl_add_u64 v[30:31], v[24:25], 0, s[18:19]
	s_nop 0
	v_addc_co_u32_e32 v179, vcc, 0, v25, vcc
	global_load_dwordx4 v[26:29], v[178:179], off nt
	s_nop 0
	global_load_dwordx4 v[30:33], v[30:31], off offset:16 nt
	s_mov_b64 s[18:19], 0x140200
	v_lshl_add_u64 v[182:183], v[24:25], 0, s[18:19]
	s_mov_b32 s4, 0x160000
	global_load_dwordx4 v[178:181], v[178:179], off offset:512 nt
	s_nop 0
	global_load_dwordx4 v[182:185], v[182:183], off offset:16 nt
	s_mov_b64 s[18:19], 0x160000
	v_add_co_u32_e32 v202, vcc, s4, v24
	v_lshl_add_u64 v[198:199], v[24:25], 0, s[18:19]
	s_nop 0
	v_addc_co_u32_e32 v203, vcc, 0, v25, vcc
	global_load_dwordx4 v[194:197], v[202:203], off nt
	s_nop 0
	global_load_dwordx4 v[198:201], v[198:199], off offset:16 nt
	s_mov_b64 s[18:19], 0x160200
	v_lshl_add_u64 v[24:25], v[24:25], 0, s[18:19]
	global_load_dwordx4 v[202:205], v[202:203], off offset:512 nt
	s_nop 0
	global_load_dwordx4 v[206:209], v[24:25], off offset:16 nt
	s_mov_b32 s4, 0xa0000
	s_waitcnt vmcnt(7)
	v_pk_fma_f32 v[24:25], v[72:73], v[6:7], v[28:29]
	v_pk_fma_f32 v[26:27], v[70:71], v[8:9], v[26:27]
	s_waitcnt vmcnt(6)
	v_pk_fma_f32 v[28:29], v[64:65], v[2:3], v[32:33]
	v_pk_fma_f32 v[30:31], v[62:63], v[4:5], v[30:31]
	v_cvt_pk_f16_f32 v25, v24, v25
	v_cvt_pk_f16_f32 v24, v26, v27
	v_cvt_pk_f16_f32 v27, v28, v29
	v_add_co_u32_e32 v28, vcc, s4, v22
	v_cvt_pk_f16_f32 v26, v30, v31
	s_nop 0
	v_addc_co_u32_e32 v29, vcc, 0, v23, vcc
	global_store_dwordx4 v[28:29], v[24:27], off
	s_waitcnt vmcnt(5)
	v_pk_fma_f32 v[30:31], v[44:45], v[10:11], v[184:185]
	v_pk_fma_f32 v[32:33], v[42:43], v[12:13], v[182:183]
	v_pk_fma_f32 v[24:25], v[52:53], v[14:15], v[180:181]
	v_pk_fma_f32 v[26:27], v[50:51], v[16:17], v[178:179]
	v_cvt_pk_f16_f32 v25, v24, v25
	v_cvt_pk_f16_f32 v24, v26, v27
	v_cvt_pk_f16_f32 v27, v30, v31
	v_cvt_pk_f16_f32 v26, v32, v33
	global_store_dwordx4 v[28:29], v[24:27], off offset:256
	s_waitcnt vmcnt(4)
	v_pk_fma_f32 v[28:29], v[48:49], v[2:3], v[200:201]
	s_mov_b32 s4, 0xb0000
	v_pk_fma_f32 v[24:25], v[56:57], v[6:7], v[196:197]
	v_pk_fma_f32 v[26:27], v[54:55], v[8:9], v[194:195]
	v_pk_fma_f32 v[30:31], v[46:47], v[4:5], v[198:199]
	v_cvt_pk_f16_f32 v25, v24, v25
	v_cvt_pk_f16_f32 v24, v26, v27
	v_cvt_pk_f16_f32 v27, v28, v29
	v_add_co_u32_e32 v28, vcc, s4, v22
	v_cvt_pk_f16_f32 v26, v30, v31
	s_nop 0
	v_addc_co_u32_e32 v29, vcc, 0, v23, vcc
	global_store_dwordx4 v[28:29], v[24:27], off
	s_waitcnt vmcnt(4)
	v_pk_fma_f32 v[22:23], v[40:41], v[14:15], v[204:205]
	s_waitcnt vmcnt(3)
	v_pk_fma_f32 v[30:31], v[34:35], v[12:13], v[206:207]
	v_pk_fma_f32 v[24:25], v[38:39], v[16:17], v[202:203]
	v_pk_fma_f32 v[26:27], v[36:37], v[10:11], v[208:209]
	v_cvt_pk_f16_f32 v23, v22, v23
	v_cvt_pk_f16_f32 v22, v24, v25
	v_cvt_pk_f16_f32 v25, v26, v27
	v_cvt_pk_f16_f32 v24, v30, v31
	global_store_dwordx4 v[28:29], v[22:25], off offset:256
	s_cbranch_execz .LBB0_402
